# qkconv conv loop: rolling 3-row window per wave (18 consecutive rows, one new row load per trip instead of three), scalar halo arithmetic, hoisted weights
# speedup vs baseline: 1.0026x; 1.0001x over previous
.LBB0_1608:
	s_or_b64 exec, exec, s[18:19]
	v_lshl_add_u32 v2, s2, 9, v128
	s_mov_b32 s0, 0x240000
	v_cmp_gt_i32_e32 vcc, s0, v2
	s_and_saveexec_b64 s[6:7], vcc
	v_readlane_b32 s36, v252, 16
	v_readlane_b32 s50, v252, 30
	v_readlane_b32 s51, v252, 31
	v_readlane_b32 s37, v252, 17
	v_readlane_b32 s38, v252, 18
	v_readlane_b32 s39, v252, 19
	v_readlane_b32 s40, v252, 20
	v_readlane_b32 s41, v252, 21
	v_readlane_b32 s42, v252, 22
	v_readlane_b32 s43, v252, 23
	v_readlane_b32 s44, v252, 24
	v_readlane_b32 s45, v252, 25
	v_readlane_b32 s46, v252, 26
	v_readlane_b32 s47, v252, 27
	v_readlane_b32 s48, v252, 28
	v_readlane_b32 s49, v252, 29
	s_cbranch_execz .LBB0_1611
	v_lshlrev_b32_e32 v0, 3, v128
	s_mov_b64 s[26:27], s[50:51]
	s_lshl_b32 s14, s22, 9
	v_lshl_add_u32 v3, s2, 12, v0
	s_lshl_b32 s15, s22, 12
	s_mov_b64 s[8:9], 0
	s_movk_i32 s16, 0x4000
	s_waitcnt vmcnt(2)
	v_mov_b32_e32 v4, 0xff
	v_mov_b32_e32 v5, 0x7ff
	v_mov_b32_e32 v6, 0x100
	v_mov_b32_e32 v7, 0x800
	v_mov_b32_e32 v1, 0
	s_mov_b64 s[10:11], 0x1000
	s_mov_b64 s[12:13], 0x2000
	s_movk_i32 s17, 0x2000
	s_movk_i32 s18, 0x1ff
	v_mov_b32_e32 v8, 0x3e000000
	s_mov_b32 s19, 0x23ffff
	v_and_b32_e32 v9, 0x3f8, v3
	v_lshlrev_b32_e32 v0, 2, v9
	v_add_u32_e32 v106, 0x1000, v0
	v_add_u32_e32 v107, 0x2000, v0
	global_load_dwordx4 v[74:77], v0, s[72:73]
	global_load_dwordx4 v[78:81], v0, s[72:73] offset:16
	global_load_dwordx4 v[82:85], v0, s[26:27]
	global_load_dwordx4 v[86:89], v0, s[26:27] offset:16
	global_load_dwordx4 v[90:93], v106, s[26:27]
	global_load_dwordx4 v[94:97], v106, s[26:27] offset:16
	global_load_dwordx4 v[98:101], v107, s[26:27]
	global_load_dwordx4 v[102:105], v107, s[26:27] offset:16
	v_lshlrev_b32_e32 v68, 1, v9
	v_cmp_lt_u32_e64 s[0:1], s18, v9
	v_readfirstlane_b32 s17, v128
	s_mul_i32 s101, s22, 0x48
	v_cndmask_b32_e64 v67, 1.0, v8, s[0:1]
	s_lshr_b32 s17, s17, 7
	s_lshl_b32 s8, s2, 2
	s_add_i32 s8, s8, s17
	s_mul_i32 s98, s8, 18
.Lqkc_chunk:
	s_cmp_lt_i32 s98, 0x4800
	s_cbranch_scc0 .LBB0_1611
	s_add_i32 s8, s98, -1
	s_max_i32 s8, s8, 0
	s_lshl_b32 s0, s8, 11
	s_add_u32 s0, s4, s0
	s_addc_u32 s1, s5, 0
	global_load_dwordx4 v[46:49], v68, s[0:1]
	s_lshl_b32 s0, s98, 11
	s_add_u32 s0, s4, s0
	s_addc_u32 s1, s5, 0
	global_load_dwordx4 v[50:53], v68, s[0:1]
	s_add_i32 s8, s98, 1
	s_lshl_b32 s0, s8, 11
	s_add_u32 s0, s4, s0
	s_addc_u32 s1, s5, 0
	global_load_dwordx4 v[42:45], v68, s[0:1]
	s_mov_b32 s100, 0
	s_waitcnt vmcnt(0)
.Lqkc_loop:
	s_add_i32 s8, s98, s100
	s_add_i32 s0, s8, 2
	s_min_i32 s0, s0, 0x47ff
	s_lshl_b32 s0, s0, 11
	s_add_u32 s0, s4, s0
	s_addc_u32 s1, s5, 0
	global_load_dwordx4 v[114:117], v68, s[0:1]
	s_cmp_lt_i32 s8, s16
	s_movk_i32 s9, 0xff
	s_cselect_b32 s9, 0x7ff, s9
	s_and_b32 s12, s8, s9
	s_lshl_b32 s10, s8, 11
	s_add_u32 s10, s88, s10
	s_addc_u32 s11, s89, 0
	s_waitcnt vmcnt(2)
	s_cmp_lg_u32 s12, 0
	s_cbranch_scc0 .Lqkc_off0_0
	v_lshlrev_b32_e32 v59, 16, v46
	v_and_b32_e32 v60, 0xffff0000, v46
	v_lshlrev_b32_e32 v61, 16, v47
	v_and_b32_e32 v62, 0xffff0000, v47
	v_lshlrev_b32_e32 v63, 16, v48
	v_and_b32_e32 v64, 0xffff0000, v48
	v_lshlrev_b32_e32 v65, 16, v49
	v_and_b32_e32 v66, 0xffff0000, v49
	v_fma_f32 v10, v82, v59, v74
	v_fma_f32 v11, v83, v60, v75
	v_fma_f32 v12, v84, v61, v76
	v_fma_f32 v13, v85, v62, v77
	v_fma_f32 v14, v86, v63, v78
	v_fma_f32 v15, v87, v64, v79
	v_fma_f32 v16, v88, v65, v80
	v_fma_f32 v17, v89, v66, v81
	s_branch .Lqkc_j0_0

.Lqkc_j0_0:
	v_lshlrev_b32_e32 v59, 16, v50
	v_and_b32_e32 v60, 0xffff0000, v50
	v_lshlrev_b32_e32 v61, 16, v51
	v_and_b32_e32 v62, 0xffff0000, v51
	v_lshlrev_b32_e32 v63, 16, v52
	v_and_b32_e32 v64, 0xffff0000, v52
	v_lshlrev_b32_e32 v65, 16, v53
	v_and_b32_e32 v66, 0xffff0000, v53
	v_fmac_f32_e32 v10, v90, v59
	v_fmac_f32_e32 v11, v91, v60
	v_fmac_f32_e32 v12, v92, v61
	v_fmac_f32_e32 v13, v93, v62
	v_fmac_f32_e32 v14, v94, v63
	v_fmac_f32_e32 v15, v95, v64
	v_fmac_f32_e32 v16, v96, v65
	v_fmac_f32_e32 v17, v97, v66
	s_cmp_lg_u32 s12, s9
	s_cbranch_scc0 .Lqkc_off2_0
	v_lshlrev_b32_e32 v59, 16, v42
	v_and_b32_e32 v60, 0xffff0000, v42
	v_lshlrev_b32_e32 v61, 16, v43
	v_and_b32_e32 v62, 0xffff0000, v43
	v_lshlrev_b32_e32 v63, 16, v44
	v_and_b32_e32 v64, 0xffff0000, v44
	v_lshlrev_b32_e32 v65, 16, v45
	v_and_b32_e32 v66, 0xffff0000, v45
	v_fmac_f32_e32 v10, v98, v59
	v_fmac_f32_e32 v11, v99, v60
	v_fmac_f32_e32 v12, v100, v61
	v_fmac_f32_e32 v13, v101, v62
	v_fmac_f32_e32 v14, v102, v63
	v_fmac_f32_e32 v15, v103, v64
	v_fmac_f32_e32 v16, v104, v65
	v_fmac_f32_e32 v17, v105, v66
.Lqkc_off2_0:
	v_mul_f32_e32 v18, 0xbfb8aa3b, v10
	v_mul_f32_e32 v19, 0xbfb8aa3b, v11
	v_mul_f32_e32 v20, 0xbfb8aa3b, v12
	v_mul_f32_e32 v21, 0xbfb8aa3b, v13
	v_mul_f32_e32 v22, 0xbfb8aa3b, v14
	v_mul_f32_e32 v23, 0xbfb8aa3b, v15
	v_mul_f32_e32 v24, 0xbfb8aa3b, v16
	v_mul_f32_e32 v25, 0xbfb8aa3b, v17
	v_exp_f32_e32 v18, v18
	v_exp_f32_e32 v19, v19
	v_exp_f32_e32 v20, v20
	v_exp_f32_e32 v21, v21
	v_exp_f32_e32 v22, v22
	v_exp_f32_e32 v23, v23
	v_exp_f32_e32 v24, v24
	v_exp_f32_e32 v25, v25
	v_add_f32_e32 v18, 1.0, v18
	v_add_f32_e32 v19, 1.0, v19
	v_add_f32_e32 v20, 1.0, v20
	v_add_f32_e32 v21, 1.0, v21
	v_add_f32_e32 v22, 1.0, v22
	v_add_f32_e32 v23, 1.0, v23
	v_add_f32_e32 v24, 1.0, v24
	v_add_f32_e32 v25, 1.0, v25
	v_rcp_f32_e32 v18, v18
	v_rcp_f32_e32 v19, v19
	v_rcp_f32_e32 v20, v20
	v_rcp_f32_e32 v21, v21
	v_rcp_f32_e32 v22, v22
	v_rcp_f32_e32 v23, v23
	v_rcp_f32_e32 v24, v24
	v_rcp_f32_e32 v25, v25
	v_mul_f32_e32 v18, v10, v18
	v_mul_f32_e32 v19, v11, v19
	v_mul_f32_e32 v20, v12, v20
	v_mul_f32_e32 v21, v13, v21
	v_mul_f32_e32 v22, v14, v22
	v_mul_f32_e32 v23, v15, v23
	v_mul_f32_e32 v24, v16, v24
	v_mul_f32_e32 v25, v17, v25
	v_mul_f32_e32 v18, v67, v18
	v_mul_f32_e32 v19, v67, v19
	v_mul_f32_e32 v20, v67, v20
	v_mul_f32_e32 v21, v67, v21
	v_mul_f32_e32 v22, v67, v22
	v_mul_f32_e32 v23, v67, v23
	v_mul_f32_e32 v24, v67, v24
	v_mul_f32_e32 v25, v67, v25
	v_cvt_pk_bf16_f32 v10, v18, v19
	v_cvt_pk_bf16_f32 v11, v20, v21
	v_cvt_pk_bf16_f32 v12, v22, v23
	v_cvt_pk_bf16_f32 v13, v24, v25
	global_store_dwordx4 v68, v[10:13], s[10:11]
	s_add_i32 s100, s100, 1
	s_cmp_eq_u32 s100, 18
	s_cbranch_scc1 .Lqkc_chunk_done
	s_add_i32 s8, s98, s100
	s_add_i32 s0, s8, 2
	s_min_i32 s0, s0, 0x47ff
	s_lshl_b32 s0, s0, 11
	s_add_u32 s0, s4, s0
	s_addc_u32 s1, s5, 0
	global_load_dwordx4 v[46:49], v68, s[0:1]
	s_cmp_lt_i32 s8, s16
	s_movk_i32 s9, 0xff
	s_cselect_b32 s9, 0x7ff, s9
	s_and_b32 s12, s8, s9
	s_lshl_b32 s10, s8, 11
	s_add_u32 s10, s88, s10
	s_addc_u32 s11, s89, 0
	s_waitcnt vmcnt(2)
	s_cmp_lg_u32 s12, 0
	s_cbranch_scc0 .Lqkc_off0_1
	v_lshlrev_b32_e32 v59, 16, v50
	v_and_b32_e32 v60, 0xffff0000, v50
	v_lshlrev_b32_e32 v61, 16, v51
	v_and_b32_e32 v62, 0xffff0000, v51
	v_lshlrev_b32_e32 v63, 16, v52
	v_and_b32_e32 v64, 0xffff0000, v52
	v_lshlrev_b32_e32 v65, 16, v53
	v_and_b32_e32 v66, 0xffff0000, v53
	v_fma_f32 v10, v82, v59, v74
	v_fma_f32 v11, v83, v60, v75
	v_fma_f32 v12, v84, v61, v76
	v_fma_f32 v13, v85, v62, v77
	v_fma_f32 v14, v86, v63, v78
	v_fma_f32 v15, v87, v64, v79
	v_fma_f32 v16, v88, v65, v80
	v_fma_f32 v17, v89, v66, v81
	s_branch .Lqkc_j0_1

.Lqkc_j0_1:
	v_lshlrev_b32_e32 v59, 16, v42
	v_and_b32_e32 v60, 0xffff0000, v42
	v_lshlrev_b32_e32 v61, 16, v43
	v_and_b32_e32 v62, 0xffff0000, v43
	v_lshlrev_b32_e32 v63, 16, v44
	v_and_b32_e32 v64, 0xffff0000, v44
	v_lshlrev_b32_e32 v65, 16, v45
	v_and_b32_e32 v66, 0xffff0000, v45
	v_fmac_f32_e32 v10, v90, v59
	v_fmac_f32_e32 v11, v91, v60
	v_fmac_f32_e32 v12, v92, v61
	v_fmac_f32_e32 v13, v93, v62
	v_fmac_f32_e32 v14, v94, v63
	v_fmac_f32_e32 v15, v95, v64
	v_fmac_f32_e32 v16, v96, v65
	v_fmac_f32_e32 v17, v97, v66
	s_cmp_lg_u32 s12, s9
	s_cbranch_scc0 .Lqkc_off2_1
	v_lshlrev_b32_e32 v59, 16, v114
	v_and_b32_e32 v60, 0xffff0000, v114
	v_lshlrev_b32_e32 v61, 16, v115
	v_and_b32_e32 v62, 0xffff0000, v115
	v_lshlrev_b32_e32 v63, 16, v116
	v_and_b32_e32 v64, 0xffff0000, v116
	v_lshlrev_b32_e32 v65, 16, v117
	v_and_b32_e32 v66, 0xffff0000, v117
	v_fmac_f32_e32 v10, v98, v59
	v_fmac_f32_e32 v11, v99, v60
	v_fmac_f32_e32 v12, v100, v61
	v_fmac_f32_e32 v13, v101, v62
	v_fmac_f32_e32 v14, v102, v63
	v_fmac_f32_e32 v15, v103, v64
	v_fmac_f32_e32 v16, v104, v65
	v_fmac_f32_e32 v17, v105, v66
.Lqkc_off2_1:
	v_mul_f32_e32 v18, 0xbfb8aa3b, v10
	v_mul_f32_e32 v19, 0xbfb8aa3b, v11
	v_mul_f32_e32 v20, 0xbfb8aa3b, v12
	v_mul_f32_e32 v21, 0xbfb8aa3b, v13
	v_mul_f32_e32 v22, 0xbfb8aa3b, v14
	v_mul_f32_e32 v23, 0xbfb8aa3b, v15
	v_mul_f32_e32 v24, 0xbfb8aa3b, v16
	v_mul_f32_e32 v25, 0xbfb8aa3b, v17
	v_exp_f32_e32 v18, v18
	v_exp_f32_e32 v19, v19
	v_exp_f32_e32 v20, v20
	v_exp_f32_e32 v21, v21
	v_exp_f32_e32 v22, v22
	v_exp_f32_e32 v23, v23
	v_exp_f32_e32 v24, v24
	v_exp_f32_e32 v25, v25
	v_add_f32_e32 v18, 1.0, v18
	v_add_f32_e32 v19, 1.0, v19
	v_add_f32_e32 v20, 1.0, v20
	v_add_f32_e32 v21, 1.0, v21
	v_add_f32_e32 v22, 1.0, v22
	v_add_f32_e32 v23, 1.0, v23
	v_add_f32_e32 v24, 1.0, v24
	v_add_f32_e32 v25, 1.0, v25
	v_rcp_f32_e32 v18, v18
	v_rcp_f32_e32 v19, v19
	v_rcp_f32_e32 v20, v20
	v_rcp_f32_e32 v21, v21
	v_rcp_f32_e32 v22, v22
	v_rcp_f32_e32 v23, v23
	v_rcp_f32_e32 v24, v24
	v_rcp_f32_e32 v25, v25
	v_mul_f32_e32 v18, v10, v18
	v_mul_f32_e32 v19, v11, v19
	v_mul_f32_e32 v20, v12, v20
	v_mul_f32_e32 v21, v13, v21
	v_mul_f32_e32 v22, v14, v22
	v_mul_f32_e32 v23, v15, v23
	v_mul_f32_e32 v24, v16, v24
	v_mul_f32_e32 v25, v17, v25
	v_mul_f32_e32 v18, v67, v18
	v_mul_f32_e32 v19, v67, v19
	v_mul_f32_e32 v20, v67, v20
	v_mul_f32_e32 v21, v67, v21
	v_mul_f32_e32 v22, v67, v22
	v_mul_f32_e32 v23, v67, v23
	v_mul_f32_e32 v24, v67, v24
	v_mul_f32_e32 v25, v67, v25
	v_cvt_pk_bf16_f32 v10, v18, v19
	v_cvt_pk_bf16_f32 v11, v20, v21
	v_cvt_pk_bf16_f32 v12, v22, v23
	v_cvt_pk_bf16_f32 v13, v24, v25
	global_store_dwordx4 v68, v[10:13], s[10:11]
	s_add_i32 s100, s100, 1
	s_cmp_eq_u32 s100, 18
	s_cbranch_scc1 .Lqkc_chunk_done
	s_add_i32 s8, s98, s100
	s_add_i32 s0, s8, 2
	s_min_i32 s0, s0, 0x47ff
	s_lshl_b32 s0, s0, 11
	s_add_u32 s0, s4, s0
	s_addc_u32 s1, s5, 0
	global_load_dwordx4 v[50:53], v68, s[0:1]
	s_cmp_lt_i32 s8, s16
	s_movk_i32 s9, 0xff
	s_cselect_b32 s9, 0x7ff, s9
	s_and_b32 s12, s8, s9
	s_lshl_b32 s10, s8, 11
	s_add_u32 s10, s88, s10
	s_addc_u32 s11, s89, 0
	s_waitcnt vmcnt(2)
	s_cmp_lg_u32 s12, 0
	s_cbranch_scc0 .Lqkc_off0_2
	v_lshlrev_b32_e32 v59, 16, v42
	v_and_b32_e32 v60, 0xffff0000, v42
	v_lshlrev_b32_e32 v61, 16, v43
	v_and_b32_e32 v62, 0xffff0000, v43
	v_lshlrev_b32_e32 v63, 16, v44
	v_and_b32_e32 v64, 0xffff0000, v44
	v_lshlrev_b32_e32 v65, 16, v45
	v_and_b32_e32 v66, 0xffff0000, v45
	v_fma_f32 v10, v82, v59, v74
	v_fma_f32 v11, v83, v60, v75
	v_fma_f32 v12, v84, v61, v76
	v_fma_f32 v13, v85, v62, v77
	v_fma_f32 v14, v86, v63, v78
	v_fma_f32 v15, v87, v64, v79
	v_fma_f32 v16, v88, v65, v80
	v_fma_f32 v17, v89, v66, v81
	s_branch .Lqkc_j0_2

.Lqkc_j0_2:
	v_lshlrev_b32_e32 v59, 16, v114
	v_and_b32_e32 v60, 0xffff0000, v114
	v_lshlrev_b32_e32 v61, 16, v115
	v_and_b32_e32 v62, 0xffff0000, v115
	v_lshlrev_b32_e32 v63, 16, v116
	v_and_b32_e32 v64, 0xffff0000, v116
	v_lshlrev_b32_e32 v65, 16, v117
	v_and_b32_e32 v66, 0xffff0000, v117
	v_fmac_f32_e32 v10, v90, v59
	v_fmac_f32_e32 v11, v91, v60
	v_fmac_f32_e32 v12, v92, v61
	v_fmac_f32_e32 v13, v93, v62
	v_fmac_f32_e32 v14, v94, v63
	v_fmac_f32_e32 v15, v95, v64
	v_fmac_f32_e32 v16, v96, v65
	v_fmac_f32_e32 v17, v97, v66
	s_cmp_lg_u32 s12, s9
	s_cbranch_scc0 .Lqkc_off2_2
	v_lshlrev_b32_e32 v59, 16, v46
	v_and_b32_e32 v60, 0xffff0000, v46
	v_lshlrev_b32_e32 v61, 16, v47
	v_and_b32_e32 v62, 0xffff0000, v47
	v_lshlrev_b32_e32 v63, 16, v48
	v_and_b32_e32 v64, 0xffff0000, v48
	v_lshlrev_b32_e32 v65, 16, v49
	v_and_b32_e32 v66, 0xffff0000, v49
	v_fmac_f32_e32 v10, v98, v59
	v_fmac_f32_e32 v11, v99, v60
	v_fmac_f32_e32 v12, v100, v61
	v_fmac_f32_e32 v13, v101, v62
	v_fmac_f32_e32 v14, v102, v63
	v_fmac_f32_e32 v15, v103, v64
	v_fmac_f32_e32 v16, v104, v65
	v_fmac_f32_e32 v17, v105, v66
.Lqkc_off2_2:
	v_mul_f32_e32 v18, 0xbfb8aa3b, v10
	v_mul_f32_e32 v19, 0xbfb8aa3b, v11
	v_mul_f32_e32 v20, 0xbfb8aa3b, v12
	v_mul_f32_e32 v21, 0xbfb8aa3b, v13
	v_mul_f32_e32 v22, 0xbfb8aa3b, v14
	v_mul_f32_e32 v23, 0xbfb8aa3b, v15
	v_mul_f32_e32 v24, 0xbfb8aa3b, v16
	v_mul_f32_e32 v25, 0xbfb8aa3b, v17
	v_exp_f32_e32 v18, v18
	v_exp_f32_e32 v19, v19
	v_exp_f32_e32 v20, v20
	v_exp_f32_e32 v21, v21
	v_exp_f32_e32 v22, v22
	v_exp_f32_e32 v23, v23
	v_exp_f32_e32 v24, v24
	v_exp_f32_e32 v25, v25
	v_add_f32_e32 v18, 1.0, v18
	v_add_f32_e32 v19, 1.0, v19
	v_add_f32_e32 v20, 1.0, v20
	v_add_f32_e32 v21, 1.0, v21
	v_add_f32_e32 v22, 1.0, v22
	v_add_f32_e32 v23, 1.0, v23
	v_add_f32_e32 v24, 1.0, v24
	v_add_f32_e32 v25, 1.0, v25
	v_rcp_f32_e32 v18, v18
	v_rcp_f32_e32 v19, v19
	v_rcp_f32_e32 v20, v20
	v_rcp_f32_e32 v21, v21
	v_rcp_f32_e32 v22, v22
	v_rcp_f32_e32 v23, v23
	v_rcp_f32_e32 v24, v24
	v_rcp_f32_e32 v25, v25
	v_mul_f32_e32 v18, v10, v18
	v_mul_f32_e32 v19, v11, v19
	v_mul_f32_e32 v20, v12, v20
	v_mul_f32_e32 v21, v13, v21
	v_mul_f32_e32 v22, v14, v22
	v_mul_f32_e32 v23, v15, v23
	v_mul_f32_e32 v24, v16, v24
	v_mul_f32_e32 v25, v17, v25
	v_mul_f32_e32 v18, v67, v18
	v_mul_f32_e32 v19, v67, v19
	v_mul_f32_e32 v20, v67, v20
	v_mul_f32_e32 v21, v67, v21
	v_mul_f32_e32 v22, v67, v22
	v_mul_f32_e32 v23, v67, v23
	v_mul_f32_e32 v24, v67, v24
	v_mul_f32_e32 v25, v67, v25
	v_cvt_pk_bf16_f32 v10, v18, v19
	v_cvt_pk_bf16_f32 v11, v20, v21
	v_cvt_pk_bf16_f32 v12, v22, v23
	v_cvt_pk_bf16_f32 v13, v24, v25
	global_store_dwordx4 v68, v[10:13], s[10:11]
	s_add_i32 s100, s100, 1
	s_cmp_eq_u32 s100, 18
	s_cbranch_scc1 .Lqkc_chunk_done
	s_add_i32 s8, s98, s100
	s_add_i32 s0, s8, 2
	s_min_i32 s0, s0, 0x47ff
	s_lshl_b32 s0, s0, 11
	s_add_u32 s0, s4, s0
	s_addc_u32 s1, s5, 0
	global_load_dwordx4 v[42:45], v68, s[0:1]
	s_cmp_lt_i32 s8, s16
	s_movk_i32 s9, 0xff
	s_cselect_b32 s9, 0x7ff, s9
	s_and_b32 s12, s8, s9
	s_lshl_b32 s10, s8, 11
	s_add_u32 s10, s88, s10
	s_addc_u32 s11, s89, 0
	s_waitcnt vmcnt(2)
	s_cmp_lg_u32 s12, 0
	s_cbranch_scc0 .Lqkc_off0_3
	v_lshlrev_b32_e32 v59, 16, v114
	v_and_b32_e32 v60, 0xffff0000, v114
	v_lshlrev_b32_e32 v61, 16, v115
	v_and_b32_e32 v62, 0xffff0000, v115
	v_lshlrev_b32_e32 v63, 16, v116
	v_and_b32_e32 v64, 0xffff0000, v116
	v_lshlrev_b32_e32 v65, 16, v117
	v_and_b32_e32 v66, 0xffff0000, v117
	v_fma_f32 v10, v82, v59, v74
	v_fma_f32 v11, v83, v60, v75
	v_fma_f32 v12, v84, v61, v76
	v_fma_f32 v13, v85, v62, v77
	v_fma_f32 v14, v86, v63, v78
	v_fma_f32 v15, v87, v64, v79
	v_fma_f32 v16, v88, v65, v80
	v_fma_f32 v17, v89, v66, v81
	s_branch .Lqkc_j0_3

.Lqkc_j0_3:
	v_lshlrev_b32_e32 v59, 16, v46
	v_and_b32_e32 v60, 0xffff0000, v46
	v_lshlrev_b32_e32 v61, 16, v47
	v_and_b32_e32 v62, 0xffff0000, v47
	v_lshlrev_b32_e32 v63, 16, v48
	v_and_b32_e32 v64, 0xffff0000, v48
	v_lshlrev_b32_e32 v65, 16, v49
	v_and_b32_e32 v66, 0xffff0000, v49
	v_fmac_f32_e32 v10, v90, v59
	v_fmac_f32_e32 v11, v91, v60
	v_fmac_f32_e32 v12, v92, v61
	v_fmac_f32_e32 v13, v93, v62
	v_fmac_f32_e32 v14, v94, v63
	v_fmac_f32_e32 v15, v95, v64
	v_fmac_f32_e32 v16, v96, v65
	v_fmac_f32_e32 v17, v97, v66
	s_cmp_lg_u32 s12, s9
	s_cbranch_scc0 .Lqkc_off2_3
	v_lshlrev_b32_e32 v59, 16, v50
	v_and_b32_e32 v60, 0xffff0000, v50
	v_lshlrev_b32_e32 v61, 16, v51
	v_and_b32_e32 v62, 0xffff0000, v51
	v_lshlrev_b32_e32 v63, 16, v52
	v_and_b32_e32 v64, 0xffff0000, v52
	v_lshlrev_b32_e32 v65, 16, v53
	v_and_b32_e32 v66, 0xffff0000, v53
	v_fmac_f32_e32 v10, v98, v59
	v_fmac_f32_e32 v11, v99, v60
	v_fmac_f32_e32 v12, v100, v61
	v_fmac_f32_e32 v13, v101, v62
	v_fmac_f32_e32 v14, v102, v63
	v_fmac_f32_e32 v15, v103, v64
	v_fmac_f32_e32 v16, v104, v65
	v_fmac_f32_e32 v17, v105, v66
.Lqkc_off2_3:
	v_mul_f32_e32 v18, 0xbfb8aa3b, v10
	v_mul_f32_e32 v19, 0xbfb8aa3b, v11
	v_mul_f32_e32 v20, 0xbfb8aa3b, v12
	v_mul_f32_e32 v21, 0xbfb8aa3b, v13
	v_mul_f32_e32 v22, 0xbfb8aa3b, v14
	v_mul_f32_e32 v23, 0xbfb8aa3b, v15
	v_mul_f32_e32 v24, 0xbfb8aa3b, v16
	v_mul_f32_e32 v25, 0xbfb8aa3b, v17
	v_exp_f32_e32 v18, v18
	v_exp_f32_e32 v19, v19
	v_exp_f32_e32 v20, v20
	v_exp_f32_e32 v21, v21
	v_exp_f32_e32 v22, v22
	v_exp_f32_e32 v23, v23
	v_exp_f32_e32 v24, v24
	v_exp_f32_e32 v25, v25
	v_add_f32_e32 v18, 1.0, v18
	v_add_f32_e32 v19, 1.0, v19
	v_add_f32_e32 v20, 1.0, v20
	v_add_f32_e32 v21, 1.0, v21
	v_add_f32_e32 v22, 1.0, v22
	v_add_f32_e32 v23, 1.0, v23
	v_add_f32_e32 v24, 1.0, v24
	v_add_f32_e32 v25, 1.0, v25
	v_rcp_f32_e32 v18, v18
	v_rcp_f32_e32 v19, v19
	v_rcp_f32_e32 v20, v20
	v_rcp_f32_e32 v21, v21
	v_rcp_f32_e32 v22, v22
	v_rcp_f32_e32 v23, v23
	v_rcp_f32_e32 v24, v24
	v_rcp_f32_e32 v25, v25
	v_mul_f32_e32 v18, v10, v18
	v_mul_f32_e32 v19, v11, v19
	v_mul_f32_e32 v20, v12, v20
	v_mul_f32_e32 v21, v13, v21
	v_mul_f32_e32 v22, v14, v22
	v_mul_f32_e32 v23, v15, v23
	v_mul_f32_e32 v24, v16, v24
	v_mul_f32_e32 v25, v17, v25
	v_mul_f32_e32 v18, v67, v18
	v_mul_f32_e32 v19, v67, v19
	v_mul_f32_e32 v20, v67, v20
	v_mul_f32_e32 v21, v67, v21
	v_mul_f32_e32 v22, v67, v22
	v_mul_f32_e32 v23, v67, v23
	v_mul_f32_e32 v24, v67, v24
	v_mul_f32_e32 v25, v67, v25
	v_cvt_pk_bf16_f32 v10, v18, v19
	v_cvt_pk_bf16_f32 v11, v20, v21
	v_cvt_pk_bf16_f32 v12, v22, v23
	v_cvt_pk_bf16_f32 v13, v24, v25
	global_store_dwordx4 v68, v[10:13], s[10:11]
	s_add_i32 s100, s100, 1
	s_cmp_eq_u32 s100, 18
	s_cbranch_scc1 .Lqkc_chunk_done
	s_branch .Lqkc_loop
.Lqkc_chunk_done:
	s_add_i32 s98, s98, s101
	s_branch .Lqkc_chunk
